# J + relaxed first-iteration vmcnt(24) waits after GEMM epilogue stores in P2/P8, dropped header vmcnt(0) in P8
# speedup vs baseline: 1.0071x; 1.0071x over previous
; #define PG8_STAGE(bufoff, gbase, voff) do { _Pragma("unroll") for (int _i = 0; _i < 2; ++_i) \
;         __builtin_amdgcn_global_load_lds((const unsigned*)((const char*)(gbase) + (voff)[_i]), (PG8_LAS unsigned*)(lds + (bufoff) + ldsw + _i * 8192), 16, 0, 0); } while (0)
; #define PG8_WAIT_V(n) asm volatile("s_waitcnt vmcnt(" #n ")" ::: "memory")
; #define PG8_BAR __builtin_amdgcn_s_barrier()
; template <class Epi, class Sched, bool ALIGN_EPI = false, bool SP2 = false>
; __device__ __forceinline__ void gemm_phase(PG8_LAS unsigned char* lds, const Gemm g, const Sched& S, const Epi& E) {
;     ...
;     for (int i = 0; i < 2; ++i) { int R, C; stage_rc(tid * 16 + i * 8192, R, C); const int Rb = Epi::PERM ? ((R & ~31) + perm32(R & 31)) : R;
;         voffA[i] = (unsigned)(R * K + C) * 2u; voffB[i] = (unsigned)(Rb * K + C) * 2u; }
;     const size_t kstep = (size_t)(BK * 2);
;     const size_t hstep = (size_t)HALF * K * 2;
;     const size_t tstep = 2 * hstep;
;     const unsigned ldsw = (unsigned)wid * 1024u;
;     const int aoff = lds_byte(wr * 64 + fr, fq * 8), boff = lds_byte(wc * 32 + fr, fq * 8);
;     ...
;         PG8_STAGE(PG8_SB(0, 0), cB, voffB); PG8_STAGE(PG8_SB(0, 1), cB + hstep, voffB); PG8_STAGE(PG8_SA(0, 0), cA, voffA); PG8_STAGE(PG8_SA(0, 1), cA + hstep, voffA);
;         if (wr == 1) PG8_BAR;
;         PG8_WAIT_V(2); PG8_BAR;
;         PG8_STAGE(PG8_SB(1, 0), cB + kstep, voffB); PG8_STAGE(PG8_SA(1, 0), cA + kstep, voffA); PG8_STAGE(PG8_SB(1, 1), cB + hstep + kstep, voffB);
;         PG8_WAIT_V(6); PG8_BAR;
.LBB0_151:
	s_lshl_b32 s15, s17, 5
	s_mov_b64 s[22:23], 0x80
	s_and_b32 s15, s15, 0x60
	s_add_i32 m0, s75, 0x18000
	v_lshl_add_u64 v[6:7], v[6:7], 0, s[22:23]
	s_lshl_b32 s14, s16, 13
	s_lshl_b32 s17, s15, 7
	s_waitcnt vmcnt(2)
	s_barrier
	global_load_lds_dwordx4 v[6:7], off
	v_lshl_add_u64 v[4:5], v[4:5], 0, s[22:23]
	s_add_i32 m0, s75, 0x1a000
	s_add_i32 s92, s75, 0x8000
	s_add_i32 s93, s75, 0xa000
	global_load_lds_dwordx4 v[4:5], off
	v_lshl_add_u64 v[0:1], v[0:1], 0, s[22:23]
	s_mov_b32 m0, s92
	s_add_u32 s36, s84, 0x40080
	global_load_lds_dwordx4 v[0:1], off
	v_lshl_add_u64 v[0:1], v[2:3], 0, s[22:23]
	s_mov_b32 m0, s93
	s_addc_u32 s37, s85, 0
	global_load_lds_dwordx4 v[0:1], off
	s_add_i32 m0, s75, 0x1c000
	v_lshl_add_u64 v[0:1], s[36:37], 0, v[132:133]
	global_load_lds_dwordx4 v[0:1], off
	v_lshl_add_u64 v[0:1], s[36:37], 0, v[128:129]
	s_add_i32 m0, s75, 0x1e000
	s_cmpk_lt_u32 s5, 0x100
	global_load_lds_dwordx4 v[0:1], off
	v_lshrrev_b32_e32 v1, 1, v9
	v_and_b32_e32 v1, 24, v1
	v_and_b32_e32 v0, 15, v9
	v_lshlrev_b32_e32 v2, 1, v1
	v_lshl_or_b32 v146, s16, 6, v0
	v_lshl_or_b32 v0, v0, 6, v2
	v_lshlrev_b32_e32 v2, 2, v9
	v_and_b32_e32 v2, 32, v2
	v_bitop3_b32 v3, v0, s14, v2 bitop3:0xde
	v_bitop3_b32 v147, v0, s17, v2 bitop3:0xde
	v_lshlrev_b32_e32 v0, 14, v13
	v_and_b32_e32 v0, 0xffff8000, v0
	v_or_b32_e32 v148, s15, v1
	v_lshl_add_u32 v0, v12, 11, v0
	v_and_b32_e32 v1, 1, v13
	v_lshl_or_b32 v0, v1, 6, v0
	v_lshl_add_u32 v136, v14, 1, v0
	v_lshlrev_b32_e32 v0, 14, v8
	v_and_b32_e32 v0, 0xffff8000, v0
	s_waitcnt vmcnt(6)
	v_lshl_add_u32 v0, v10, 11, v0
	v_and_b32_e32 v1, 1, v8
	s_cselect_b64 s[38:39], -1, 0
	v_lshl_or_b32 v0, v1, 6, v0
	s_add_i32 s94, 0, 0x10000
	s_add_i32 s95, 0, 0x14000
	s_sext_i32_i8 s97, s18
	v_mov_b32_e32 v137, v133
	v_lshl_add_u32 v138, v11, 1, v0
	v_mov_b32_e32 v139, v133
	v_mov_b64_e32 v[140:141], 0x300
	v_mov_b64_e32 v[142:143], 0x2ff
	s_mov_b64 s[40:41], 0x100
	v_add_u32_e32 v149, s94, v147
	v_add_u32_e32 v150, s95, v147
	v_add_u32_e32 v151, 0, v3
	s_movk_i32 s96, 0x1800
	s_barrier
	s_mov_b32 s100, 0
	s_branch .LBB0_154

; #define PG8_STAGE(bufoff, gbase, voff) do { _Pragma("unroll") for (int _i = 0; _i < 2; ++_i) \
;         __builtin_amdgcn_global_load_lds((const unsigned*)((const char*)(gbase) + (voff)[_i]), (PG8_LAS unsigned*)(lds + (bufoff) + ldsw + _i * 8192), 16, 0, 0); } while (0)
; #define PG8_LDA(dst, b, h) do { _Pragma("unroll") for (int m = 0; m < 4; ++m) _Pragma("unroll") for (int k = 0; k < 2; ++k) dst[m][k] = *(const PG8_LAS bf16x8*)(lds + PG8_SA(b, h) + aoff + m * 2048 + k * 1024); } while (0)
; #define PG8_LDB(dst, b, h) do { _Pragma("unroll") for (int n = 0; n < 2; ++n) _Pragma("unroll") for (int k = 0; k < 2; ++k) dst[n][k] = *(const PG8_LAS bf16x8*)(lds + PG8_SB(b, h) + boff + n * 2048 + k * 1024); } while (0)
; #define PG8_MMA(ai, bj, At, Bt) do { __builtin_amdgcn_s_setprio(1); _Pragma("unroll") for (int m = 0; m < 4; ++m) _Pragma("unroll") for (int n = 0; n < 2; ++n) _Pragma("unroll") for (int k = 0; k < 2; ++k) \
;         acc[ai][bj][m][n] = __builtin_amdgcn_mfma_f32_16x16x32_bf16(Bt[n][k], At[m][k], acc[ai][bj][m][n], 0, 0, 0); __builtin_amdgcn_s_setprio(0); } while (0)
; #define PG8_WAIT_V(n) asm volatile("s_waitcnt vmcnt(" #n ")" ::: "memory")
; #define PG8_WAIT_L(n) asm volatile("s_waitcnt lgkmcnt(" #n ")" ::: "memory")
; #define PG8_BAR __builtin_amdgcn_s_barrier()
; #define PG8_SCHED __builtin_amdgcn_sched_barrier(0)
; template <class Epi, class Sched, bool ALIGN_EPI = false, bool SP2 = false>
; __device__ __forceinline__ void gemm_phase(PG8_LAS unsigned char* lds, const Gemm g, const Sched& S, const Epi& E) {
;     ...
;             PG8_LDB(B0, 0, 0); PG8_LDB(B1, 0, 1); PG8_SCHED; PG8_LDA(At, 0, 0); PG8_STAGE(PG8_SA(1, 1), a1 + hstep, voffA);
;             PG8_WAIT_V(8); PG8_WAIT_L(0); PG8_BAR; PG8_MMA(0, 0, At, B0); PG8_MMA(0, 1, At, B1); PG8_BAR; PG8_SCHED;
;             PG8_LDA(At, 0, 1); PG8_STAGE(PG8_SB(0, 0), b2, voffB); PG8_STAGE(PG8_SB(0, 1), b2 + hstep, voffB); PG8_STAGE(PG8_SA(0, 0), a2, voffA);
;             PG8_WAIT_V(8); PG8_WAIT_L(0); PG8_BAR; PG8_MMA(1, 0, At, B0); PG8_MMA(1, 1, At, B1); PG8_BAR; PG8_SCHED;
.LBB0_157:
	ds_read_b128 v[152:155], v149
	ds_read_b128 v[156:159], v149 offset:1024
	ds_read_b128 v[160:163], v149 offset:2048
	ds_read_b128 v[164:167], v149 offset:3072
	ds_read_b128 v[168:171], v150
	ds_read_b128 v[172:175], v150 offset:1024
	ds_read_b128 v[176:179], v150 offset:2048
	ds_read_b128 v[180:183], v150 offset:3072
	s_add_u32 s14, s76, 0xfffc0080
	s_addc_u32 s15, s77, -1
	s_cmp_eq_u32 s16, 12
	s_cselect_b32 s85, s45, s15
	s_cselect_b32 s84, vcc_lo, s14
	s_cselect_b32 s19, s43, s33
	s_cselect_b32 s18, vcc_hi, s5
	v_lshl_add_u64 v[144:145], s[76:77], 0, v[136:137]
	s_add_i32 m0, s75, 0xc000
	ds_read_b128 v[184:187], v151
	ds_read_b128 v[188:191], v151 offset:1024
	ds_read_b128 v[192:195], v151 offset:2048
	ds_read_b128 v[196:199], v151 offset:3072
	ds_read_b128 v[200:203], v151 offset:4096
	ds_read_b128 v[204:207], v151 offset:5120
	ds_read_b128 v[218:221], v151 offset:6144
	ds_read_b128 v[222:225], v151 offset:7168
	global_load_lds_dwordx4 v[144:145], off
	v_lshl_add_u64 v[144:145], s[76:77], 0, v[138:139]
	s_add_i32 m0, s75, 0xe000
	s_nop 0
	global_load_lds_dwordx4 v[144:145], off
	s_cmp_eq_u32 s100, 0
	s_cbranch_scc1 .Lw8_2a
	s_waitcnt vmcnt(24)
	s_branch .Lwd_2a
.Lw8_2a:
	s_waitcnt vmcnt(8)
.Lwd_2a:
	s_waitcnt lgkmcnt(0)
	s_barrier
	s_setprio 1
	s_waitcnt lgkmcnt(0)
	v_mfma_f32_16x16x32_bf16 v[124:127], v[152:155], v[184:187], v[124:127]
	v_mfma_f32_16x16x32_bf16 v[120:123], v[160:163], v[184:187], v[120:123]
	v_mfma_f32_16x16x32_bf16 v[112:115], v[152:155], v[192:195], v[112:115]
	v_mfma_f32_16x16x32_bf16 v[104:107], v[160:163], v[192:195], v[104:107]
	v_mfma_f32_16x16x32_bf16 v[96:99], v[152:155], v[200:203], v[96:99]
	v_mfma_f32_16x16x32_bf16 v[88:91], v[160:163], v[200:203], v[88:91]
	v_mfma_f32_16x16x32_bf16 v[80:83], v[152:155], v[218:221], v[80:83]
	v_mfma_f32_16x16x32_bf16 v[72:75], v[160:163], v[218:221], v[72:75]
	v_mfma_f32_16x16x32_bf16 v[124:127], v[156:159], v[188:191], v[124:127]
	v_mfma_f32_16x16x32_bf16 v[120:123], v[164:167], v[188:191], v[120:123]
	v_mfma_f32_16x16x32_bf16 v[112:115], v[156:159], v[196:199], v[112:115]
	v_mfma_f32_16x16x32_bf16 v[104:107], v[164:167], v[196:199], v[104:107]
	v_mfma_f32_16x16x32_bf16 v[96:99], v[156:159], v[204:207], v[96:99]
	v_mfma_f32_16x16x32_bf16 v[88:91], v[164:167], v[204:207], v[88:91]
	v_mfma_f32_16x16x32_bf16 v[80:83], v[156:159], v[222:225], v[80:83]
	v_mfma_f32_16x16x32_bf16 v[72:75], v[164:167], v[222:225], v[72:75]
	s_setprio 0
	s_setprio 1
	v_mfma_f32_16x16x32_bf16 v[116:119], v[168:171], v[184:187], v[116:119]
	v_mfma_f32_16x16x32_bf16 v[108:111], v[176:179], v[184:187], v[108:111]
	v_mfma_f32_16x16x32_bf16 v[100:103], v[168:171], v[192:195], v[100:103]
	v_mfma_f32_16x16x32_bf16 v[92:95], v[176:179], v[192:195], v[92:95]
	v_mfma_f32_16x16x32_bf16 v[84:87], v[168:171], v[200:203], v[84:87]
	v_mfma_f32_16x16x32_bf16 v[76:79], v[176:179], v[200:203], v[76:79]
	v_mfma_f32_16x16x32_bf16 v[68:71], v[168:171], v[218:221], v[68:71]
	v_mfma_f32_16x16x32_bf16 v[64:67], v[176:179], v[218:221], v[64:67]
	v_mfma_f32_16x16x32_bf16 v[116:119], v[172:175], v[188:191], v[116:119]
	v_mfma_f32_16x16x32_bf16 v[108:111], v[180:183], v[188:191], v[108:111]
	v_mfma_f32_16x16x32_bf16 v[100:103], v[172:175], v[196:199], v[100:103]
	v_mfma_f32_16x16x32_bf16 v[92:95], v[180:183], v[196:199], v[92:95]
	v_mfma_f32_16x16x32_bf16 v[84:87], v[172:175], v[204:207], v[84:87]
	v_mfma_f32_16x16x32_bf16 v[76:79], v[180:183], v[204:207], v[76:79]
	v_mfma_f32_16x16x32_bf16 v[68:71], v[172:175], v[222:225], v[68:71]
	v_mfma_f32_16x16x32_bf16 v[64:67], v[180:183], v[222:225], v[64:67]
	s_setprio 0
	s_barrier
	s_add_i32 s14, s94, s86
	v_lshl_add_u64 v[144:145], s[18:19], 0, v[132:133]
	s_mov_b32 m0, s14
	ds_read_b128 v[184:187], v151 offset:16384
	ds_read_b128 v[188:191], v151 offset:17408
	ds_read_b128 v[192:195], v151 offset:18432
	ds_read_b128 v[196:199], v151 offset:19456
	ds_read_b128 v[200:203], v151 offset:20480
	ds_read_b128 v[204:207], v151 offset:21504
	ds_read_b128 v[218:221], v151 offset:22528
	ds_read_b128 v[222:225], v151 offset:23552
	global_load_lds_dwordx4 v[144:145], off
	s_add_i32 m0, s14, 0x2000
	s_add_u32 s14, s18, 0x40000
	v_lshl_add_u64 v[226:227], s[18:19], 0, v[128:129]
	s_addc_u32 s15, s19, 0
	s_add_i32 s17, s95, s86
	global_load_lds_dwordx4 v[226:227], off
	v_lshl_add_u64 v[228:229], s[14:15], 0, v[132:133]
	s_mov_b32 m0, s17
	v_lshl_add_u64 v[230:231], s[84:85], 0, v[130:131]
	global_load_lds_dwordx4 v[228:229], off
	v_lshl_add_u64 v[228:229], s[14:15], 0, v[128:129]
	s_add_i32 m0, s17, 0x2000
	s_nop 0
	global_load_lds_dwordx4 v[228:229], off
	v_lshl_add_u64 v[228:229], s[84:85], 0, v[134:135]
	s_mov_b32 m0, s75
	s_nop 0
	global_load_lds_dwordx4 v[228:229], off
	s_mov_b32 m0, s88
	s_nop 0
	global_load_lds_dwordx4 v[230:231], off
	s_cmp_eq_u32 s100, 0
	s_cbranch_scc1 .Lw8_2b
	s_waitcnt vmcnt(24)
	s_branch .Lwd_2b

; #define PG8_STAGE(bufoff, gbase, voff) do { _Pragma("unroll") for (int _i = 0; _i < 2; ++_i) \
;         __builtin_amdgcn_global_load_lds((const unsigned*)((const char*)(gbase) + (voff)[_i]), (PG8_LAS unsigned*)(lds + (bufoff) + ldsw + _i * 8192), 16, 0, 0); } while (0)
; #define PG8_LDA(dst, b, h) do { _Pragma("unroll") for (int m = 0; m < 4; ++m) _Pragma("unroll") for (int k = 0; k < 2; ++k) dst[m][k] = *(const PG8_LAS bf16x8*)(lds + PG8_SA(b, h) + aoff + m * 2048 + k * 1024); } while (0)
; #define PG8_LDB(dst, b, h) do { _Pragma("unroll") for (int n = 0; n < 2; ++n) _Pragma("unroll") for (int k = 0; k < 2; ++k) dst[n][k] = *(const PG8_LAS bf16x8*)(lds + PG8_SB(b, h) + boff + n * 2048 + k * 1024); } while (0)
; #define PG8_MMA(ai, bj, At, Bt) do { __builtin_amdgcn_s_setprio(1); _Pragma("unroll") for (int m = 0; m < 4; ++m) _Pragma("unroll") for (int n = 0; n < 2; ++n) _Pragma("unroll") for (int k = 0; k < 2; ++k) \
;         acc[ai][bj][m][n] = __builtin_amdgcn_mfma_f32_16x16x32_bf16(Bt[n][k], At[m][k], acc[ai][bj][m][n], 0, 0, 0); __builtin_amdgcn_s_setprio(0); } while (0)
; #define PG8_WAIT_V(n) asm volatile("s_waitcnt vmcnt(" #n ")" ::: "memory")
; #define PG8_WAIT_L(n) asm volatile("s_waitcnt lgkmcnt(" #n ")" ::: "memory")
; #define PG8_BAR __builtin_amdgcn_s_barrier()
; #define PG8_SCHED __builtin_amdgcn_sched_barrier(0)
; template <class Epi, class Sched, bool ALIGN_EPI = false, bool SP2 = false>
; __device__ __forceinline__ void gemm_phase(PG8_LAS unsigned char* lds, const Gemm g, const Sched& S, const Epi& E) {
;     ...
;             PG8_WAIT_V(8); PG8_WAIT_L(0); PG8_BAR; PG8_MMA(1, 0, At, B0); PG8_MMA(1, 1, At, B1); PG8_BAR; PG8_SCHED;
;             PG8_LDB(B0, 1, 0); PG8_LDB(B1, 1, 1); PG8_SCHED; PG8_LDA(At, 1, 0); PG8_STAGE(PG8_SA(0, 1), a2 + hstep, voffA);
;             PG8_WAIT_V(8); PG8_WAIT_L(0); PG8_BAR; PG8_MMA(0, 0, At, B0); PG8_MMA(0, 1, At, B1); PG8_BAR; PG8_SCHED;
.Lwd_2b:
	s_mov_b32 s100, 0
	s_waitcnt lgkmcnt(0)
	s_barrier
	s_setprio 1
	s_waitcnt lgkmcnt(0)
	v_mfma_f32_16x16x32_bf16 v[60:63], v[152:155], v[184:187], v[60:63]
	v_mfma_f32_16x16x32_bf16 v[56:59], v[160:163], v[184:187], v[56:59]
	v_mfma_f32_16x16x32_bf16 v[48:51], v[152:155], v[192:195], v[48:51]
	v_mfma_f32_16x16x32_bf16 v[40:43], v[160:163], v[192:195], v[40:43]
	v_mfma_f32_16x16x32_bf16 v[32:35], v[152:155], v[200:203], v[32:35]
	v_mfma_f32_16x16x32_bf16 v[24:27], v[160:163], v[200:203], v[24:27]
	v_mfma_f32_16x16x32_bf16 v[16:19], v[152:155], v[218:221], v[16:19]
	v_mfma_f32_16x16x32_bf16 v[8:11], v[160:163], v[218:221], v[8:11]
	v_mfma_f32_16x16x32_bf16 v[60:63], v[156:159], v[188:191], v[60:63]
	v_mfma_f32_16x16x32_bf16 v[56:59], v[164:167], v[188:191], v[56:59]
	v_mfma_f32_16x16x32_bf16 v[48:51], v[156:159], v[196:199], v[48:51]
	v_mfma_f32_16x16x32_bf16 v[40:43], v[164:167], v[196:199], v[40:43]
	v_mfma_f32_16x16x32_bf16 v[32:35], v[156:159], v[204:207], v[32:35]
	v_mfma_f32_16x16x32_bf16 v[24:27], v[164:167], v[204:207], v[24:27]
	v_mfma_f32_16x16x32_bf16 v[16:19], v[156:159], v[222:225], v[16:19]
	v_mfma_f32_16x16x32_bf16 v[8:11], v[164:167], v[222:225], v[8:11]
	s_setprio 0
	s_setprio 1
	v_mfma_f32_16x16x32_bf16 v[52:55], v[168:171], v[184:187], v[52:55]
	v_mfma_f32_16x16x32_bf16 v[44:47], v[176:179], v[184:187], v[44:47]
	v_mfma_f32_16x16x32_bf16 v[36:39], v[168:171], v[192:195], v[36:39]
	v_mfma_f32_16x16x32_bf16 v[28:31], v[176:179], v[192:195], v[28:31]
	v_mfma_f32_16x16x32_bf16 v[20:23], v[168:171], v[200:203], v[20:23]
	v_mfma_f32_16x16x32_bf16 v[12:15], v[176:179], v[200:203], v[12:15]
	v_mfma_f32_16x16x32_bf16 v[4:7], v[168:171], v[218:221], v[4:7]
	v_mfma_f32_16x16x32_bf16 v[0:3], v[176:179], v[218:221], v[0:3]
	v_mfma_f32_16x16x32_bf16 v[52:55], v[172:175], v[188:191], v[52:55]
	v_mfma_f32_16x16x32_bf16 v[44:47], v[180:183], v[188:191], v[44:47]
	v_mfma_f32_16x16x32_bf16 v[36:39], v[172:175], v[196:199], v[36:39]
	v_mfma_f32_16x16x32_bf16 v[28:31], v[180:183], v[196:199], v[28:31]
	v_mfma_f32_16x16x32_bf16 v[20:23], v[172:175], v[204:207], v[20:23]
	v_mfma_f32_16x16x32_bf16 v[12:15], v[180:183], v[204:207], v[12:15]
	v_mfma_f32_16x16x32_bf16 v[4:7], v[172:175], v[222:225], v[4:7]
	v_mfma_f32_16x16x32_bf16 v[0:3], v[180:183], v[222:225], v[0:3]
	s_setprio 0
	s_barrier
	s_add_i32 s17, 0, 0x18000
	s_add_i32 s24, 0, 0x1c000
	v_add_u32_e32 v164, s17, v147
	v_add_u32_e32 v180, s24, v147
	ds_read_b128 v[152:155], v164
	ds_read_b128 v[156:159], v164 offset:1024
	ds_read_b128 v[160:163], v164 offset:2048
	ds_read_b128 v[164:167], v164 offset:3072
	ds_read_b128 v[168:171], v180
	ds_read_b128 v[172:175], v180 offset:1024
	ds_read_b128 v[176:179], v180 offset:2048
	ds_read_b128 v[180:183], v180 offset:3072
	s_add_u32 s14, s84, 0x40000
	s_addc_u32 s15, s85, 0
	s_mov_b32 m0, s89
	v_lshl_add_u64 v[232:233], s[14:15], 0, v[134:135]
	ds_read_b128 v[184:187], v151 offset:32768
	ds_read_b128 v[188:191], v151 offset:33792
	ds_read_b128 v[192:195], v151 offset:34816
	ds_read_b128 v[196:199], v151 offset:35840
	ds_read_b128 v[200:203], v151 offset:36864
	ds_read_b128 v[204:207], v151 offset:37888
	ds_read_b128 v[218:221], v151 offset:38912
	ds_read_b128 v[222:225], v151 offset:39936
	global_load_lds_dwordx4 v[232:233], off
	v_lshl_add_u64 v[232:233], s[14:15], 0, v[130:131]
	s_mov_b32 m0, s90
	s_nop 0
	global_load_lds_dwordx4 v[232:233], off
	s_waitcnt vmcnt(8)
	s_waitcnt lgkmcnt(0)
	s_barrier
	s_setprio 1
	s_waitcnt lgkmcnt(0)
	v_mfma_f32_16x16x32_bf16 v[124:127], v[152:155], v[184:187], v[124:127]
	v_mfma_f32_16x16x32_bf16 v[120:123], v[160:163], v[184:187], v[120:123]
	v_mfma_f32_16x16x32_bf16 v[112:115], v[152:155], v[192:195], v[112:115]
	v_mfma_f32_16x16x32_bf16 v[104:107], v[160:163], v[192:195], v[104:107]
	v_mfma_f32_16x16x32_bf16 v[96:99], v[152:155], v[200:203], v[96:99]
	v_mfma_f32_16x16x32_bf16 v[88:91], v[160:163], v[200:203], v[88:91]
	v_mfma_f32_16x16x32_bf16 v[80:83], v[152:155], v[218:221], v[80:83]
	v_mfma_f32_16x16x32_bf16 v[72:75], v[160:163], v[218:221], v[72:75]
	v_mfma_f32_16x16x32_bf16 v[124:127], v[156:159], v[188:191], v[124:127]
	v_mfma_f32_16x16x32_bf16 v[120:123], v[164:167], v[188:191], v[120:123]
	v_mfma_f32_16x16x32_bf16 v[112:115], v[156:159], v[196:199], v[112:115]
	v_mfma_f32_16x16x32_bf16 v[104:107], v[164:167], v[196:199], v[104:107]
	v_mfma_f32_16x16x32_bf16 v[96:99], v[156:159], v[204:207], v[96:99]
	v_mfma_f32_16x16x32_bf16 v[88:91], v[164:167], v[204:207], v[88:91]
	v_mfma_f32_16x16x32_bf16 v[80:83], v[156:159], v[222:225], v[80:83]
	v_mfma_f32_16x16x32_bf16 v[72:75], v[164:167], v[222:225], v[72:75]
	s_setprio 0
	s_setprio 1
	v_mfma_f32_16x16x32_bf16 v[116:119], v[168:171], v[184:187], v[116:119]
	v_mfma_f32_16x16x32_bf16 v[108:111], v[176:179], v[184:187], v[108:111]
	v_mfma_f32_16x16x32_bf16 v[100:103], v[168:171], v[192:195], v[100:103]
	v_mfma_f32_16x16x32_bf16 v[92:95], v[176:179], v[192:195], v[92:95]
	v_mfma_f32_16x16x32_bf16 v[84:87], v[168:171], v[200:203], v[84:87]
	v_mfma_f32_16x16x32_bf16 v[76:79], v[176:179], v[200:203], v[76:79]
	v_mfma_f32_16x16x32_bf16 v[68:71], v[168:171], v[218:221], v[68:71]
	v_mfma_f32_16x16x32_bf16 v[64:67], v[176:179], v[218:221], v[64:67]
	v_mfma_f32_16x16x32_bf16 v[116:119], v[172:175], v[188:191], v[116:119]
	v_mfma_f32_16x16x32_bf16 v[108:111], v[180:183], v[188:191], v[108:111]
	v_mfma_f32_16x16x32_bf16 v[100:103], v[172:175], v[196:199], v[100:103]
	v_mfma_f32_16x16x32_bf16 v[92:95], v[180:183], v[196:199], v[92:95]
	v_mfma_f32_16x16x32_bf16 v[84:87], v[172:175], v[204:207], v[84:87]
	v_mfma_f32_16x16x32_bf16 v[76:79], v[180:183], v[204:207], v[76:79]
	v_mfma_f32_16x16x32_bf16 v[68:71], v[172:175], v[222:225], v[68:71]
	v_mfma_f32_16x16x32_bf16 v[64:67], v[180:183], v[222:225], v[64:67]
	s_setprio 0
	s_barrier
; #define PG8_STAGE(bufoff, gbase, voff) do { _Pragma("unroll") for (int _i = 0; _i < 2; ++_i) \
;         __builtin_amdgcn_global_load_lds((const unsigned*)((const char*)(gbase) + (voff)[_i]), (PG8_LAS unsigned*)(lds + (bufoff) + ldsw + _i * 8192), 16, 0, 0); } while (0)
; #define PG8_LDA(dst, b, h) do { _Pragma("unroll") for (int m = 0; m < 4; ++m) _Pragma("unroll") for (int k = 0; k < 2; ++k) dst[m][k] = *(const PG8_LAS bf16x8*)(lds + PG8_SA(b, h) + aoff + m * 2048 + k * 1024); } while (0)
; #define PG8_MMA(ai, bj, At, Bt) do { __builtin_amdgcn_s_setprio(1); _Pragma("unroll") for (int m = 0; m < 4; ++m) _Pragma("unroll") for (int n = 0; n < 2; ++n) _Pragma("unroll") for (int k = 0; k < 2; ++k) \
;         acc[ai][bj][m][n] = __builtin_amdgcn_mfma_f32_16x16x32_bf16(Bt[n][k], At[m][k], acc[ai][bj][m][n], 0, 0, 0); __builtin_amdgcn_s_setprio(0); } while (0)
; #define PG8_WAIT_V(n) asm volatile("s_waitcnt vmcnt(" #n ")" ::: "memory")
; #define PG8_WAIT_L(n) asm volatile("s_waitcnt lgkmcnt(" #n ")" ::: "memory")
; #define PG8_BAR __builtin_amdgcn_s_barrier()
; #define PG8_SCHED __builtin_amdgcn_sched_barrier(0)
; template <class Epi, class Sched, bool ALIGN_EPI = false, bool SP2 = false>
; __device__ __forceinline__ void gemm_phase(PG8_LAS unsigned char* lds, const Gemm g, const Sched& S, const Epi& E) {
;     ...
;         for (int t = 0; t < nt; t += 2) {
;             const bool last = (t == nt - 2);
;     ...
;             PG8_LDA(At, 1, 1); PG8_STAGE(PG8_SB(1, 0), b3, voffB); PG8_STAGE(PG8_SB(1, 1), b3 + hstep, voffB); PG8_STAGE(PG8_SA(1, 0), a3, voffA);
;             PG8_WAIT_V(8); PG8_WAIT_L(0); PG8_BAR; PG8_MMA(1, 0, At, B0); PG8_MMA(1, 1, At, B1); PG8_BAR; PG8_SCHED;
	s_add_i32 s14, s17, s86
	v_lshl_add_u64 v[144:145], v[144:145], 0, s[22:23]
	s_mov_b32 m0, s14
	ds_read_b128 v[184:187], v151 offset:49152
	ds_read_b128 v[188:191], v151 offset:50176
	ds_read_b128 v[192:195], v151 offset:51200
	ds_read_b128 v[196:199], v151 offset:52224
	ds_read_b128 v[200:203], v151 offset:53248
	ds_read_b128 v[204:207], v151 offset:54272
	ds_read_b128 v[218:221], v151 offset:55296
	ds_read_b128 v[222:225], v151 offset:56320
	global_load_lds_dwordx4 v[144:145], off
	s_add_i32 m0, s14, 0x2000
	s_add_u32 s14, s18, 0x40080
	v_lshl_add_u64 v[144:145], v[226:227], 0, s[22:23]
	s_addc_u32 s15, s19, 0
	s_add_i32 s17, s24, s86
	global_load_lds_dwordx4 v[144:145], off
	v_lshl_add_u64 v[144:145], s[14:15], 0, v[132:133]
	s_mov_b32 m0, s17
	s_nop 0
	global_load_lds_dwordx4 v[144:145], off
	v_lshl_add_u64 v[144:145], s[14:15], 0, v[128:129]
	s_add_i32 m0, s17, 0x2000
	s_nop 0
	global_load_lds_dwordx4 v[144:145], off
	v_lshl_add_u64 v[144:145], v[228:229], 0, s[22:23]
	s_mov_b32 m0, s92
	s_nop 0
	global_load_lds_dwordx4 v[144:145], off
	v_lshl_add_u64 v[144:145], v[230:231], 0, s[22:23]
	s_mov_b32 m0, s93
	s_nop 0
	global_load_lds_dwordx4 v[144:145], off
	s_waitcnt vmcnt(8)
	s_waitcnt lgkmcnt(0)
	s_barrier
	s_setprio 1
	s_waitcnt lgkmcnt(0)
	v_mfma_f32_16x16x32_bf16 v[60:63], v[152:155], v[184:187], v[60:63]
	v_mfma_f32_16x16x32_bf16 v[56:59], v[160:163], v[184:187], v[56:59]
	v_mfma_f32_16x16x32_bf16 v[48:51], v[152:155], v[192:195], v[48:51]
	v_mfma_f32_16x16x32_bf16 v[40:43], v[160:163], v[192:195], v[40:43]
	v_mfma_f32_16x16x32_bf16 v[32:35], v[152:155], v[200:203], v[32:35]
	v_mfma_f32_16x16x32_bf16 v[24:27], v[160:163], v[200:203], v[24:27]
	v_mfma_f32_16x16x32_bf16 v[16:19], v[152:155], v[218:221], v[16:19]
	v_mfma_f32_16x16x32_bf16 v[8:11], v[160:163], v[218:221], v[8:11]
	v_mfma_f32_16x16x32_bf16 v[60:63], v[156:159], v[188:191], v[60:63]
	v_mfma_f32_16x16x32_bf16 v[56:59], v[164:167], v[188:191], v[56:59]
	v_mfma_f32_16x16x32_bf16 v[48:51], v[156:159], v[196:199], v[48:51]
	v_mfma_f32_16x16x32_bf16 v[40:43], v[164:167], v[196:199], v[40:43]
	v_mfma_f32_16x16x32_bf16 v[32:35], v[156:159], v[204:207], v[32:35]
	v_mfma_f32_16x16x32_bf16 v[24:27], v[164:167], v[204:207], v[24:27]
	v_mfma_f32_16x16x32_bf16 v[16:19], v[156:159], v[222:225], v[16:19]
	v_mfma_f32_16x16x32_bf16 v[8:11], v[164:167], v[222:225], v[8:11]
	s_setprio 0
	s_setprio 1
	v_mfma_f32_16x16x32_bf16 v[52:55], v[168:171], v[184:187], v[52:55]
	v_mfma_f32_16x16x32_bf16 v[44:47], v[176:179], v[184:187], v[44:47]
	v_mfma_f32_16x16x32_bf16 v[36:39], v[168:171], v[192:195], v[36:39]
	v_mfma_f32_16x16x32_bf16 v[28:31], v[176:179], v[192:195], v[28:31]
	v_mfma_f32_16x16x32_bf16 v[20:23], v[168:171], v[200:203], v[20:23]
	v_mfma_f32_16x16x32_bf16 v[12:15], v[176:179], v[200:203], v[12:15]
	v_mfma_f32_16x16x32_bf16 v[4:7], v[168:171], v[218:221], v[4:7]
	v_mfma_f32_16x16x32_bf16 v[0:3], v[176:179], v[218:221], v[0:3]
	v_mfma_f32_16x16x32_bf16 v[52:55], v[172:175], v[188:191], v[52:55]
	v_mfma_f32_16x16x32_bf16 v[44:47], v[180:183], v[188:191], v[44:47]
	v_mfma_f32_16x16x32_bf16 v[36:39], v[172:175], v[196:199], v[36:39]
	v_mfma_f32_16x16x32_bf16 v[28:31], v[180:183], v[196:199], v[28:31]
	v_mfma_f32_16x16x32_bf16 v[20:23], v[172:175], v[204:207], v[20:23]
	v_mfma_f32_16x16x32_bf16 v[12:15], v[180:183], v[204:207], v[12:15]
	v_mfma_f32_16x16x32_bf16 v[4:7], v[172:175], v[222:225], v[4:7]
	v_mfma_f32_16x16x32_bf16 v[0:3], v[180:183], v[222:225], v[0:3]
	s_setprio 0
	s_barrier
	s_add_i32 s16, s16, 2
	s_add_u32 s76, s76, 0x100
	s_addc_u32 s77, s77, 0
	s_add_u32 s5, s5, 0x100
	s_addc_u32 s33, s33, 0
	s_cmp_gt_u32 s16, 13
	s_cbranch_scc0 .LBB0_157
	s_and_b64 vcc, exec, s[38:39]
	s_cbranch_vccz .LBB0_160
	s_barrier
; __device__ __forceinline__ unsigned cvt_pk_bf16(float lo, float hi) { unsigned r; asm volatile("v_cvt_pk_bf16_f32 %0, %1, %2" : "=v"(r) : "v"(lo), "v"(hi)); return r; }
; __device__ __forceinline__ void st16_wt(void* p, u32x4 v) { asm volatile("global_store_dwordx4 %0, %1, off sc1\n\ts_nop 1" :: "v"(p), "v"(v) : "memory"); }
;     __device__ __forceinline__ void operator()(const f32x4 (&acc)[2][2][4][2], const Unit& u, int wr, int wc, int fr, int fq) const {
;         const int row0 = u.pm * BM + wr * 64 + fr; int colt = u.pn * BM; bf16_t* base = O;
;         float sc = 1.f; if (split_cols) { const int t = colt / split_cols; base += (size_t)t * split_stride; colt -= t * split_cols; if (t == 0) sc = scale0; }
;         const int col0 = colt + wc * 32 + 8 * fq, bcol0 = u.pn * BM + wc * 32 + 8 * fq;
;         f32x4 bv[2][2];
; #pragma unroll
;         for (int bj = 0; bj < 2; ++bj)
; #pragma unroll
;             for (int n = 0; n < 2; ++n) bv[bj][n] = bias ? *(const f32x4*)(bias + bcol0 + bj * HALF + 4 * n) : (f32x4){0.f, 0.f, 0.f, 0.f};
; #pragma unroll
;         for (int ai = 0; ai < 2; ++ai)
; #pragma unroll
;             for (int m = 0; m < 4; ++m) { bf16_t* rowp = base + (size_t)(row0 + ai * HALF + m * 16) * ldc + col0;
; #pragma unroll
;                 for (int bj = 0; bj < 2; ++bj) { f32x4 v0 = acc[ai][bj][m][0] + bv[bj][0], v1 = acc[ai][bj][m][1] + bv[bj][1];
;                     if (ACT == 1) { f32x2 a = gelu_pk((f32x2){v0[0], v0[1]}), b = gelu_pk((f32x2){v0[2], v0[3]}), c = gelu_pk((f32x2){v1[0], v1[1]}), d = gelu_pk((f32x2){v1[2], v1[3]});
;                         v0 = (f32x4){a.x, a.y, b.x, b.y}; v1 = (f32x4){c.x, c.y, d.x, d.y}; }
;                     v0 = v0 * sc; v1 = v1 * sc; u32x4 w; w.x = cvt_pk_bf16(v0[0], v0[1]); w.y = cvt_pk_bf16(v0[2], v0[3]); w.z = cvt_pk_bf16(v1[0], v1[1]); w.w = cvt_pk_bf16(v1[2], v1[3]);
;                     st16_wt(rowp + bj * HALF, w); } }
.LBB0_160:
	v_lshl_or_b32 v144, s97, 8, v148
	v_ashrrev_i32_e32 v145, 31, v144
	v_lshl_add_u32 v156, s74, 8, v146
	v_lshl_add_u64 v[144:145], v[144:145], 1, s[20:21]
	v_cvt_pk_bf16_f32 v123, v122, v123
	v_cvt_pk_bf16_f32 v122, v120, v121
	v_cvt_pk_bf16_f32 v120, v124, v125
	v_cvt_pk_bf16_f32 v121, v126, v127
	v_mad_i64_i32 v[152:153], s[14:15], v156, s96, v[144:145]
	global_store_dwordx4 v[152:153], v[120:123], off sc1
	s_nop 1
	v_cvt_pk_bf16_f32 v111, v110, v111
	v_cvt_pk_bf16_f32 v110, v108, v109
	v_cvt_pk_bf16_f32 v108, v116, v117
	v_cvt_pk_bf16_f32 v109, v118, v119
	v_lshl_add_u64 v[116:117], v[152:153], 0, s[40:41]
	global_store_dwordx4 v[116:117], v[108:111], off sc1
	s_nop 1
	v_or_b32_e32 v108, 16, v156
	v_cvt_pk_bf16_f32 v107, v106, v107
	v_cvt_pk_bf16_f32 v106, v104, v105
	v_cvt_pk_bf16_f32 v104, v112, v113
	v_cvt_pk_bf16_f32 v105, v114, v115
	v_mad_i64_i32 v[108:109], s[14:15], v108, s96, v[144:145]
	global_store_dwordx4 v[108:109], v[104:107], off sc1
	s_nop 1
	v_cvt_pk_bf16_f32 v95, v94, v95
	v_cvt_pk_bf16_f32 v94, v92, v93
	v_cvt_pk_bf16_f32 v92, v100, v101
	v_cvt_pk_bf16_f32 v93, v102, v103
	v_lshl_add_u64 v[100:101], v[108:109], 0, s[40:41]
	global_store_dwordx4 v[100:101], v[92:95], off sc1
	s_nop 1
	v_or_b32_e32 v92, 32, v156
	v_cvt_pk_bf16_f32 v91, v90, v91
	v_cvt_pk_bf16_f32 v90, v88, v89
	v_cvt_pk_bf16_f32 v88, v96, v97
	v_cvt_pk_bf16_f32 v89, v98, v99
	v_mad_i64_i32 v[92:93], s[14:15], v92, s96, v[144:145]
	global_store_dwordx4 v[92:93], v[88:91], off sc1
	s_nop 1
	v_cvt_pk_bf16_f32 v79, v78, v79
	v_cvt_pk_bf16_f32 v78, v76, v77
	v_cvt_pk_bf16_f32 v76, v84, v85
	v_cvt_pk_bf16_f32 v77, v86, v87
	v_lshl_add_u64 v[84:85], v[92:93], 0, s[40:41]
	global_store_dwordx4 v[84:85], v[76:79], off sc1
	s_nop 1
	v_or_b32_e32 v76, 48, v156
	v_cvt_pk_bf16_f32 v75, v74, v75
	v_cvt_pk_bf16_f32 v74, v72, v73
	v_cvt_pk_bf16_f32 v72, v80, v81
	v_cvt_pk_bf16_f32 v73, v82, v83
	v_mad_i64_i32 v[76:77], s[14:15], v76, s96, v[144:145]
	global_store_dwordx4 v[76:77], v[72:75], off sc1
	s_nop 1
	v_cvt_pk_bf16_f32 v67, v66, v67
	v_cvt_pk_bf16_f32 v66, v64, v65
	v_cvt_pk_bf16_f32 v64, v68, v69
	v_cvt_pk_bf16_f32 v65, v70, v71
	v_lshl_add_u64 v[68:69], v[76:77], 0, s[40:41]
	global_store_dwordx4 v[68:69], v[64:67], off sc1
	s_nop 1
	v_add_u32_e32 v64, 0x80, v156
	v_cvt_pk_bf16_f32 v59, v58, v59
	v_cvt_pk_bf16_f32 v58, v56, v57
	v_cvt_pk_bf16_f32 v56, v60, v61
	v_cvt_pk_bf16_f32 v57, v62, v63
	v_mad_i64_i32 v[64:65], s[14:15], v64, s96, v[144:145]
	global_store_dwordx4 v[64:65], v[56:59], off sc1
	s_nop 1
	v_cvt_pk_bf16_f32 v47, v46, v47
	v_cvt_pk_bf16_f32 v46, v44, v45
	v_cvt_pk_bf16_f32 v44, v52, v53
	v_cvt_pk_bf16_f32 v45, v54, v55
	v_lshl_add_u64 v[52:53], v[64:65], 0, s[40:41]
	global_store_dwordx4 v[52:53], v[44:47], off sc1
	s_nop 1
	v_add_u32_e32 v44, 0x90, v156
	v_cvt_pk_bf16_f32 v43, v42, v43
	v_cvt_pk_bf16_f32 v42, v40, v41
	v_cvt_pk_bf16_f32 v40, v48, v49
	v_cvt_pk_bf16_f32 v41, v50, v51
	v_mad_i64_i32 v[44:45], s[14:15], v44, s96, v[144:145]
	global_store_dwordx4 v[44:45], v[40:43], off sc1
	s_nop 1
	v_cvt_pk_bf16_f32 v31, v30, v31
	v_cvt_pk_bf16_f32 v30, v28, v29
	v_cvt_pk_bf16_f32 v28, v36, v37
	v_cvt_pk_bf16_f32 v29, v38, v39
	v_lshl_add_u64 v[36:37], v[44:45], 0, s[40:41]
	global_store_dwordx4 v[36:37], v[28:31], off sc1
	s_nop 1
	v_add_u32_e32 v28, 0xa0, v156
	v_cvt_pk_bf16_f32 v27, v26, v27
	v_cvt_pk_bf16_f32 v26, v24, v25
	v_cvt_pk_bf16_f32 v24, v32, v33
	v_cvt_pk_bf16_f32 v25, v34, v35
	v_mad_i64_i32 v[28:29], s[14:15], v28, s96, v[144:145]
	global_store_dwordx4 v[28:29], v[24:27], off sc1
	s_nop 1
	v_cvt_pk_bf16_f32 v15, v14, v15
	v_cvt_pk_bf16_f32 v14, v12, v13
	v_cvt_pk_bf16_f32 v12, v20, v21
	v_cvt_pk_bf16_f32 v13, v22, v23
	v_lshl_add_u64 v[20:21], v[28:29], 0, s[40:41]
	global_store_dwordx4 v[20:21], v[12:15], off sc1
	s_nop 1
	v_add_u32_e32 v12, 0xb0, v156
	v_cvt_pk_bf16_f32 v11, v10, v11
	v_cvt_pk_bf16_f32 v10, v8, v9
	v_cvt_pk_bf16_f32 v8, v16, v17
	v_cvt_pk_bf16_f32 v9, v18, v19
	v_mad_i64_i32 v[12:13], s[14:15], v12, s96, v[144:145]
	global_store_dwordx4 v[12:13], v[8:11], off sc1
	s_nop 1
	v_cvt_pk_bf16_f32 v3, v2, v3
	v_cvt_pk_bf16_f32 v2, v0, v1
	v_cvt_pk_bf16_f32 v0, v4, v5
	v_cvt_pk_bf16_f32 v1, v6, v7
	v_lshl_add_u64 v[4:5], v[12:13], 0, s[40:41]
	s_andn2_b64 vcc, exec, s[36:37]
	global_store_dwordx4 v[4:5], v[0:3], off sc1
	s_mov_b32 s100, 1
	s_nop 1
	s_mov_b64 s[18:19], -1
	s_cbranch_vccnz .LBB0_153
	s_andn2_b64 vcc, exec, s[0:1]
	s_cbranch_vccnz .LBB0_152
	s_barrier
	s_branch .LBB0_152

; #define PG8_STAGE(bufoff, gbase, voff) do { _Pragma("unroll") for (int _i = 0; _i < 2; ++_i) \
;         __builtin_amdgcn_global_load_lds((const unsigned*)((const char*)(gbase) + (voff)[_i]), (PG8_LAS unsigned*)(lds + (bufoff) + ldsw + _i * 8192), 16, 0, 0); } while (0)
; #define PG8_WAIT_V(n) asm volatile("s_waitcnt vmcnt(" #n ")" ::: "memory")
; #define PG8_BAR __builtin_amdgcn_s_barrier()
; template <class Epi, class Sched, bool ALIGN_EPI = false, bool SP2 = false>
; __device__ __forceinline__ void gemm_phase(PG8_LAS unsigned char* lds, const Gemm g, const Sched& S, const Epi& E) {
;     ...
;     for (int i = 0; i < 2; ++i) { int R, C; stage_rc(tid * 16 + i * 8192, R, C); const int Rb = Epi::PERM ? ((R & ~31) + perm32(R & 31)) : R;
;         voffA[i] = (unsigned)(R * K + C) * 2u; voffB[i] = (unsigned)(Rb * K + C) * 2u; }
;     const size_t kstep = (size_t)(BK * 2);
;     const size_t hstep = (size_t)HALF * K * 2;
;     const size_t tstep = 2 * hstep;
;     const unsigned ldsw = (unsigned)wid * 1024u;
;     const int aoff = lds_byte(wr * 64 + fr, fq * 8), boff = lds_byte(wc * 32 + fr, fq * 8);
;     ...
;         PG8_STAGE(PG8_SB(0, 0), cB, voffB); PG8_STAGE(PG8_SB(0, 1), cB + hstep, voffB); PG8_STAGE(PG8_SA(0, 0), cA, voffA); PG8_STAGE(PG8_SA(0, 1), cA + hstep, voffA);
;         if (wr == 1) PG8_BAR;
;         PG8_WAIT_V(2); PG8_BAR;
;         PG8_STAGE(PG8_SB(1, 0), cB + kstep, voffB); PG8_STAGE(PG8_SA(1, 0), cA + kstep, voffA); PG8_STAGE(PG8_SB(1, 1), cB + hstep + kstep, voffB);
;         PG8_WAIT_V(6); PG8_BAR;
.Lp8_sig_done:
	s_mov_b64 exec, s[100:101]
	global_load_lds_dwordx4 v[6:7], off
	v_lshl_add_u64 v[2:3], v[2:3], 0, s[46:47]
	s_add_i32 m0, s61, 0x1a000
	s_add_i32 s78, s61, 0x8000
	s_add_i32 s79, s61, 0xa000
	global_load_lds_dwordx4 v[2:3], off
	v_lshl_add_u64 v[0:1], v[0:1], 0, s[46:47]
	s_mov_b32 m0, s78
	s_add_u32 s14, s40, 0x40080
	global_load_lds_dwordx4 v[0:1], off
	v_lshl_add_u64 v[0:1], v[4:5], 0, s[46:47]
	s_mov_b32 m0, s79
	s_addc_u32 s15, s41, 0
	global_load_lds_dwordx4 v[0:1], off
	s_add_i32 m0, s61, 0x1c000
	v_lshl_add_u64 v[0:1], s[14:15], 0, v[162:163]
	global_load_lds_dwordx4 v[0:1], off
	v_lshl_add_u64 v[0:1], s[14:15], 0, v[166:167]
	s_add_i32 m0, s61, 0x1e000
	s_cmpk_lt_u32 s16, 0x100
	global_load_lds_dwordx4 v[0:1], off
	v_lshrrev_b32_e32 v1, 1, v8
	v_and_b32_e32 v170, 24, v1
	v_and_b32_e32 v0, 15, v8
	v_lshlrev_b32_e32 v1, 1, v170
	v_lshl_or_b32 v171, s18, 6, v0
	v_lshl_or_b32 v0, v0, 6, v1
	v_lshlrev_b32_e32 v1, 2, v8
	v_and_b32_e32 v1, 32, v1
	v_bitop3_b32 v2, v0, s17, v1 bitop3:0xde
	v_bitop3_b32 v197, v0, s24, v1 bitop3:0xde
	v_lshlrev_b32_e32 v0, 14, v9
	v_and_b32_e32 v0, 0xffff8000, v0
	v_lshl_add_u32 v0, v10, 11, v0
	v_and_b32_e32 v1, 1, v9
	v_lshl_or_b32 v0, v1, 6, v0
	v_lshl_add_u32 v176, v11, 1, v0
	v_lshlrev_b32_e32 v0, 14, v12
	v_and_b32_e32 v0, 0xffff8000, v0
	s_waitcnt vmcnt(6)
	v_lshl_add_u32 v0, v13, 11, v0
	v_and_b32_e32 v1, 1, v12
	s_cselect_b64 s[48:49], -1, 0
	v_lshlrev_b32_e32 v168, 2, v170
	v_lshl_or_b32 v0, v1, 6, v0
	s_add_i32 s80, 0, 0x10000
	s_add_i32 s81, 0, 0x14000
	v_lshl_add_u64 v[172:173], s[64:65], 0, v[168:169]
	v_lshl_add_u64 v[174:175], s[62:63], 0, v[168:169]
	v_mov_b32_e32 v177, v169
	v_lshl_add_u32 v178, v14, 1, v0
	v_mov_b32_e32 v179, v169
	v_mov_b64_e32 v[180:181], 0x400
	v_mov_b64_e32 v[182:183], 0x3ff
	v_add_u32_e32 v198, s80, v197
	v_add_u32_e32 v199, s81, v197
	v_add_u32_e32 v200, 0, v2
	s_mov_b32 s50, 0x3e38aa3b
	s_lshl_b32 s82, s19, 2
	v_lshlrev_b32_e32 v168, 2, v170
	v_mov_b32_e32 v201, 0x358637bd
	s_barrier
	s_mov_b32 s100, 0
	s_branch .LBB0_630

; template <class Epi, class Sched, bool ALIGN_EPI = false, bool SP2 = false>
; __device__ __forceinline__ void gemm_phase(PG8_LAS unsigned char* lds, const Gemm g, const Sched& S, const Epi& E) {
;     ...
;         const bool has_next = S.next(ui + 1, nxt);
;         const char* nA = has_next ? (const char*)g.A + (size_t)nxt.pm * tstep : cA; const char* nB = has_next ? (const char*)g.Bt + (size_t)nxt.pn * tstep : cB;
;     ...
; #pragma unroll
;         for (int a = 0; a < 2; ++a)
; #pragma unroll
;             for (int b = 0; b < 2; ++b)
; #pragma unroll
;                 for (int m = 0; m < 4; ++m)
; #pragma unroll
;                     for (int n = 0; n < 2; ++n) acc[a][b][m][n] = (f32x4){0.f, 0.f, 0.f, 0.f};
;         cur = nxt; cA = nA; cB = nB; ++ui;
.LBB0_636:
	s_ashr_i32 s55, s54, 31
	s_lshl_b64 s[14:15], s[54:55], 19
	s_add_u32 s56, s12, s14
	s_addc_u32 s57, s13, s15
	s_and_b64 s[14:15], s[36:37], exec
	s_cselect_b32 s55, s57, s39
	s_cselect_b32 s68, s56, s38
	s_ashr_i32 s53, s52, 31
	s_lshl_b64 s[14:15], s[52:53], 19
	s_add_u32 s58, s70, s14
	s_addc_u32 s59, s71, s15
	s_and_b64 s[14:15], s[36:37], exec
	s_cselect_b32 s53, s59, s41
	s_cselect_b32 s69, s58, s40
	s_add_u32 s38, s38, 0x40080
	s_addc_u32 s39, s39, 0
	s_add_u32 s72, s40, 0x100
	v_mov_b32_e32 v0, 0
	s_addc_u32 s33, s41, 0
	s_mov_b32 s16, -2
	v_mov_b32_e32 v1, v0
	v_mov_b64_e32 v[2:3], 0
	v_mov_b64_e32 v[4:5], 0
	v_mov_b64_e32 v[6:7], 0
	v_mov_b64_e32 v[16:17], 0
	v_mov_b64_e32 v[18:19], 0
	v_mov_b64_e32 v[20:21], 0
	v_mov_b64_e32 v[22:23], 0
	v_mov_b64_e32 v[32:33], 0
	v_mov_b64_e32 v[34:35], 0
	v_mov_b64_e32 v[36:37], 0
	v_mov_b64_e32 v[38:39], 0
	v_mov_b64_e32 v[48:49], 0
	v_mov_b64_e32 v[50:51], 0
	v_mov_b64_e32 v[52:53], 0
	v_mov_b64_e32 v[54:55], 0
	v_mov_b64_e32 v[8:9], 0
	v_mov_b64_e32 v[10:11], 0
	v_mov_b64_e32 v[12:13], 0
	v_mov_b64_e32 v[14:15], 0
	v_mov_b64_e32 v[24:25], 0
	v_mov_b64_e32 v[26:27], 0
	v_mov_b64_e32 v[28:29], 0
	v_mov_b64_e32 v[30:31], 0
	v_mov_b64_e32 v[40:41], 0
	v_mov_b64_e32 v[42:43], 0
	v_mov_b64_e32 v[44:45], 0
	v_mov_b64_e32 v[46:47], 0
	v_mov_b64_e32 v[56:57], 0
	v_mov_b64_e32 v[58:59], 0
	v_mov_b64_e32 v[60:61], 0
	v_mov_b64_e32 v[62:63], 0
	v_mov_b64_e32 v[64:65], 0
	v_mov_b64_e32 v[66:67], 0
	v_mov_b64_e32 v[68:69], 0
	v_mov_b64_e32 v[70:71], 0
	v_mov_b64_e32 v[88:89], 0
	v_mov_b64_e32 v[90:91], 0
	v_mov_b64_e32 v[92:93], 0
	v_mov_b64_e32 v[94:95], 0
	v_mov_b64_e32 v[120:121], 0
	v_mov_b64_e32 v[122:123], 0
	v_mov_b64_e32 v[124:125], 0
	v_mov_b64_e32 v[126:127], 0
	v_mov_b64_e32 v[144:145], 0
	v_mov_b64_e32 v[146:147], 0
	v_mov_b64_e32 v[148:149], 0
	v_mov_b64_e32 v[150:151], 0
	v_mov_b64_e32 v[76:77], 0
	v_mov_b64_e32 v[78:79], 0
	v_mov_b64_e32 v[80:81], 0
	v_mov_b64_e32 v[82:83], 0
	v_mov_b64_e32 v[104:105], 0
	v_mov_b64_e32 v[106:107], 0
	v_mov_b64_e32 v[108:109], 0
	v_mov_b64_e32 v[110:111], 0
	v_mov_b64_e32 v[132:133], 0
	v_mov_b64_e32 v[134:135], 0
	v_mov_b64_e32 v[136:137], 0
	v_mov_b64_e32 v[138:139], 0
	v_mov_b64_e32 v[152:153], 0
	v_mov_b64_e32 v[154:155], 0
	v_mov_b64_e32 v[156:157], 0
	v_mov_b64_e32 v[158:159], 0
.LBB0_637:
	ds_read_b128 v[72:75], v198
	ds_read_b128 v[84:87], v198 offset:1024
	ds_read_b128 v[96:99], v198 offset:2048
	ds_read_b128 v[100:103], v198 offset:3072
	ds_read_b128 v[112:115], v199
	ds_read_b128 v[116:119], v199 offset:1024
	ds_read_b128 v[128:131], v199 offset:2048
	ds_read_b128 v[140:143], v199 offset:3072
	s_add_u32 s14, s38, 0xfffc0080
	s_addc_u32 s15, s39, -1
	s_cmp_eq_u32 s16, 12
	s_cselect_b32 s41, s55, s15
	s_cselect_b32 s40, s68, s14
	s_cselect_b32 s19, s53, s33
	s_cselect_b32 s18, s69, s72
	v_lshl_add_u64 v[206:207], s[38:39], 0, v[176:177]
	s_add_i32 m0, s61, 0xc000
	ds_read_b128 v[184:187], v200
	ds_read_b128 v[188:191], v200 offset:1024
	ds_read_b128 v[192:195], v200 offset:2048
	ds_read_b128 v[202:205], v200 offset:3072
	ds_read_b128 v[218:221], v200 offset:4096
	ds_read_b128 v[222:225], v200 offset:5120
	ds_read_b128 v[226:229], v200 offset:6144
	ds_read_b128 v[230:233], v200 offset:7168
	global_load_lds_dwordx4 v[206:207], off
	v_lshl_add_u64 v[206:207], s[38:39], 0, v[178:179]
	s_add_i32 m0, s61, 0xe000
	s_nop 0
	global_load_lds_dwordx4 v[206:207], off
	s_cmp_eq_u32 s100, 0
	s_cbranch_scc1 .Lw8_8a
	s_waitcnt vmcnt(24)
	s_branch .Lwd_8a

; #define PG8_STAGE(bufoff, gbase, voff) do { _Pragma("unroll") for (int _i = 0; _i < 2; ++_i) \
;         __builtin_amdgcn_global_load_lds((const unsigned*)((const char*)(gbase) + (voff)[_i]), (PG8_LAS unsigned*)(lds + (bufoff) + ldsw + _i * 8192), 16, 0, 0); } while (0)
; #define PG8_LDA(dst, b, h) do { _Pragma("unroll") for (int m = 0; m < 4; ++m) _Pragma("unroll") for (int k = 0; k < 2; ++k) dst[m][k] = *(const PG8_LAS bf16x8*)(lds + PG8_SA(b, h) + aoff + m * 2048 + k * 1024); } while (0)
; #define PG8_MMA(ai, bj, At, Bt) do { __builtin_amdgcn_s_setprio(1); _Pragma("unroll") for (int m = 0; m < 4; ++m) _Pragma("unroll") for (int n = 0; n < 2; ++n) _Pragma("unroll") for (int k = 0; k < 2; ++k) \
;         acc[ai][bj][m][n] = __builtin_amdgcn_mfma_f32_16x16x32_bf16(Bt[n][k], At[m][k], acc[ai][bj][m][n], 0, 0, 0); __builtin_amdgcn_s_setprio(0); } while (0)
; #define PG8_WAIT_V(n) asm volatile("s_waitcnt vmcnt(" #n ")" ::: "memory")
; #define PG8_WAIT_L(n) asm volatile("s_waitcnt lgkmcnt(" #n ")" ::: "memory")
; #define PG8_BAR __builtin_amdgcn_s_barrier()
; #define PG8_SCHED __builtin_amdgcn_sched_barrier(0)
; template <class Epi, class Sched, bool ALIGN_EPI = false, bool SP2 = false>
; __device__ __forceinline__ void gemm_phase(PG8_LAS unsigned char* lds, const Gemm g, const Sched& S, const Epi& E) {
;     ...
;             PG8_WAIT_V(8); PG8_WAIT_L(0); PG8_BAR; PG8_MMA(0, 0, At, B0); PG8_MMA(0, 1, At, B1); PG8_BAR; PG8_SCHED;
;             PG8_LDA(At, 0, 1); PG8_STAGE(PG8_SB(0, 0), b2, voffB); PG8_STAGE(PG8_SB(0, 1), b2 + hstep, voffB); PG8_STAGE(PG8_SA(0, 0), a2, voffA);
;             PG8_WAIT_V(8); PG8_WAIT_L(0); PG8_BAR; PG8_MMA(1, 0, At, B0); PG8_MMA(1, 1, At, B1); PG8_BAR; PG8_SCHED;
.Lwd_8a:
	s_waitcnt lgkmcnt(0)
	s_barrier
	s_setprio 1
	s_waitcnt lgkmcnt(0)
	v_mfma_f32_16x16x32_bf16 v[156:159], v[72:75], v[184:187], v[156:159]
	v_mfma_f32_16x16x32_bf16 v[152:155], v[96:99], v[184:187], v[152:155]
	v_mfma_f32_16x16x32_bf16 v[136:139], v[72:75], v[192:195], v[136:139]
	v_mfma_f32_16x16x32_bf16 v[132:135], v[96:99], v[192:195], v[132:135]
	v_mfma_f32_16x16x32_bf16 v[108:111], v[72:75], v[218:221], v[108:111]
	v_mfma_f32_16x16x32_bf16 v[104:107], v[96:99], v[218:221], v[104:107]
	v_mfma_f32_16x16x32_bf16 v[80:83], v[72:75], v[226:229], v[80:83]
	v_mfma_f32_16x16x32_bf16 v[76:79], v[96:99], v[226:229], v[76:79]
	v_mfma_f32_16x16x32_bf16 v[156:159], v[84:87], v[188:191], v[156:159]
	v_mfma_f32_16x16x32_bf16 v[152:155], v[100:103], v[188:191], v[152:155]
	v_mfma_f32_16x16x32_bf16 v[136:139], v[84:87], v[202:205], v[136:139]
	v_mfma_f32_16x16x32_bf16 v[132:135], v[100:103], v[202:205], v[132:135]
	v_mfma_f32_16x16x32_bf16 v[108:111], v[84:87], v[222:225], v[108:111]
	v_mfma_f32_16x16x32_bf16 v[104:107], v[100:103], v[222:225], v[104:107]
	v_mfma_f32_16x16x32_bf16 v[80:83], v[84:87], v[230:233], v[80:83]
	v_mfma_f32_16x16x32_bf16 v[76:79], v[100:103], v[230:233], v[76:79]
	s_setprio 0
	s_setprio 1
	v_mfma_f32_16x16x32_bf16 v[148:151], v[112:115], v[184:187], v[148:151]
	v_mfma_f32_16x16x32_bf16 v[144:147], v[128:131], v[184:187], v[144:147]
	v_mfma_f32_16x16x32_bf16 v[124:127], v[112:115], v[192:195], v[124:127]
	v_mfma_f32_16x16x32_bf16 v[120:123], v[128:131], v[192:195], v[120:123]
	v_mfma_f32_16x16x32_bf16 v[92:95], v[112:115], v[218:221], v[92:95]
	v_mfma_f32_16x16x32_bf16 v[88:91], v[128:131], v[218:221], v[88:91]
	v_mfma_f32_16x16x32_bf16 v[68:71], v[112:115], v[226:229], v[68:71]
	v_mfma_f32_16x16x32_bf16 v[64:67], v[128:131], v[226:229], v[64:67]
	v_mfma_f32_16x16x32_bf16 v[148:151], v[116:119], v[188:191], v[148:151]
	v_mfma_f32_16x16x32_bf16 v[144:147], v[140:143], v[188:191], v[144:147]
	v_mfma_f32_16x16x32_bf16 v[124:127], v[116:119], v[202:205], v[124:127]
	v_mfma_f32_16x16x32_bf16 v[120:123], v[140:143], v[202:205], v[120:123]
	v_mfma_f32_16x16x32_bf16 v[92:95], v[116:119], v[222:225], v[92:95]
	v_mfma_f32_16x16x32_bf16 v[88:91], v[140:143], v[222:225], v[88:91]
	v_mfma_f32_16x16x32_bf16 v[68:71], v[116:119], v[230:233], v[68:71]
	v_mfma_f32_16x16x32_bf16 v[64:67], v[140:143], v[230:233], v[64:67]
	s_setprio 0
	s_barrier
	s_add_i32 s14, s80, s51
	v_lshl_add_u64 v[206:207], s[18:19], 0, v[162:163]
	s_mov_b32 m0, s14
	ds_read_b128 v[184:187], v200 offset:16384
	ds_read_b128 v[188:191], v200 offset:17408
	ds_read_b128 v[192:195], v200 offset:18432
	ds_read_b128 v[202:205], v200 offset:19456
	ds_read_b128 v[218:221], v200 offset:20480
	ds_read_b128 v[222:225], v200 offset:21504
	ds_read_b128 v[226:229], v200 offset:22528
	ds_read_b128 v[230:233], v200 offset:23552
	global_load_lds_dwordx4 v[206:207], off
	s_add_i32 m0, s14, 0x2000
	s_add_u32 s14, s18, 0x40000
	v_lshl_add_u64 v[234:235], s[18:19], 0, v[166:167]
	s_addc_u32 s15, s19, 0
	s_add_i32 s17, s81, s51
	global_load_lds_dwordx4 v[234:235], off
	v_lshl_add_u64 v[236:237], s[14:15], 0, v[162:163]
	s_mov_b32 m0, s17
	v_lshl_add_u64 v[238:239], s[40:41], 0, v[164:165]
	global_load_lds_dwordx4 v[236:237], off
	v_lshl_add_u64 v[236:237], s[14:15], 0, v[166:167]
	s_add_i32 m0, s17, 0x2000
	s_nop 0
	global_load_lds_dwordx4 v[236:237], off
	v_lshl_add_u64 v[236:237], s[40:41], 0, v[160:161]
	s_mov_b32 m0, s61
	s_nop 0
	global_load_lds_dwordx4 v[236:237], off
	s_mov_b32 m0, s67
	s_nop 0
	global_load_lds_dwordx4 v[238:239], off
	s_cmp_eq_u32 s100, 0
	s_cbranch_scc1 .Lw8_8b
	s_waitcnt vmcnt(24)
	s_branch .Lwd_8b

; #define PG8_STAGE(bufoff, gbase, voff) do { _Pragma("unroll") for (int _i = 0; _i < 2; ++_i) \
;         __builtin_amdgcn_global_load_lds((const unsigned*)((const char*)(gbase) + (voff)[_i]), (PG8_LAS unsigned*)(lds + (bufoff) + ldsw + _i * 8192), 16, 0, 0); } while (0)
; #define PG8_LDA(dst, b, h) do { _Pragma("unroll") for (int m = 0; m < 4; ++m) _Pragma("unroll") for (int k = 0; k < 2; ++k) dst[m][k] = *(const PG8_LAS bf16x8*)(lds + PG8_SA(b, h) + aoff + m * 2048 + k * 1024); } while (0)
; #define PG8_LDB(dst, b, h) do { _Pragma("unroll") for (int n = 0; n < 2; ++n) _Pragma("unroll") for (int k = 0; k < 2; ++k) dst[n][k] = *(const PG8_LAS bf16x8*)(lds + PG8_SB(b, h) + boff + n * 2048 + k * 1024); } while (0)
; #define PG8_MMA(ai, bj, At, Bt) do { __builtin_amdgcn_s_setprio(1); _Pragma("unroll") for (int m = 0; m < 4; ++m) _Pragma("unroll") for (int n = 0; n < 2; ++n) _Pragma("unroll") for (int k = 0; k < 2; ++k) \
;         acc[ai][bj][m][n] = __builtin_amdgcn_mfma_f32_16x16x32_bf16(Bt[n][k], At[m][k], acc[ai][bj][m][n], 0, 0, 0); __builtin_amdgcn_s_setprio(0); } while (0)
; #define PG8_WAIT_V(n) asm volatile("s_waitcnt vmcnt(" #n ")" ::: "memory")
; #define PG8_WAIT_L(n) asm volatile("s_waitcnt lgkmcnt(" #n ")" ::: "memory")
; #define PG8_BAR __builtin_amdgcn_s_barrier()
; #define PG8_SCHED __builtin_amdgcn_sched_barrier(0)
; template <class Epi, class Sched, bool ALIGN_EPI = false, bool SP2 = false>
; __device__ __forceinline__ void gemm_phase(PG8_LAS unsigned char* lds, const Gemm g, const Sched& S, const Epi& E) {
;     ...
;             PG8_WAIT_V(8); PG8_WAIT_L(0); PG8_BAR; PG8_MMA(1, 0, At, B0); PG8_MMA(1, 1, At, B1); PG8_BAR; PG8_SCHED;
;             PG8_LDB(B0, 1, 0); PG8_LDB(B1, 1, 1); PG8_SCHED; PG8_LDA(At, 1, 0); PG8_STAGE(PG8_SA(0, 1), a2 + hstep, voffA);
;             PG8_WAIT_V(8); PG8_WAIT_L(0); PG8_BAR; PG8_MMA(0, 0, At, B0); PG8_MMA(0, 1, At, B1); PG8_BAR; PG8_SCHED;
.Lwd_8b:
	s_mov_b32 s100, 0
	s_waitcnt lgkmcnt(0)
	s_barrier
	s_setprio 1
	s_waitcnt lgkmcnt(0)
	v_mfma_f32_16x16x32_bf16 v[60:63], v[72:75], v[184:187], v[60:63]
	v_mfma_f32_16x16x32_bf16 v[56:59], v[96:99], v[184:187], v[56:59]
	v_mfma_f32_16x16x32_bf16 v[44:47], v[72:75], v[192:195], v[44:47]
	v_mfma_f32_16x16x32_bf16 v[40:43], v[96:99], v[192:195], v[40:43]
	v_mfma_f32_16x16x32_bf16 v[28:31], v[72:75], v[218:221], v[28:31]
	v_mfma_f32_16x16x32_bf16 v[24:27], v[96:99], v[218:221], v[24:27]
	v_mfma_f32_16x16x32_bf16 v[12:15], v[72:75], v[226:229], v[12:15]
	v_mfma_f32_16x16x32_bf16 v[8:11], v[96:99], v[226:229], v[8:11]
	v_mfma_f32_16x16x32_bf16 v[60:63], v[84:87], v[188:191], v[60:63]
	v_mfma_f32_16x16x32_bf16 v[56:59], v[100:103], v[188:191], v[56:59]
	v_mfma_f32_16x16x32_bf16 v[44:47], v[84:87], v[202:205], v[44:47]
	v_mfma_f32_16x16x32_bf16 v[40:43], v[100:103], v[202:205], v[40:43]
	v_mfma_f32_16x16x32_bf16 v[28:31], v[84:87], v[222:225], v[28:31]
	v_mfma_f32_16x16x32_bf16 v[24:27], v[100:103], v[222:225], v[24:27]
	v_mfma_f32_16x16x32_bf16 v[12:15], v[84:87], v[230:233], v[12:15]
	v_mfma_f32_16x16x32_bf16 v[8:11], v[100:103], v[230:233], v[8:11]
	s_setprio 0
	s_setprio 1
	v_mfma_f32_16x16x32_bf16 v[52:55], v[112:115], v[184:187], v[52:55]
	v_mfma_f32_16x16x32_bf16 v[48:51], v[128:131], v[184:187], v[48:51]
	v_mfma_f32_16x16x32_bf16 v[36:39], v[112:115], v[192:195], v[36:39]
	v_mfma_f32_16x16x32_bf16 v[32:35], v[128:131], v[192:195], v[32:35]
	v_mfma_f32_16x16x32_bf16 v[20:23], v[112:115], v[218:221], v[20:23]
	v_mfma_f32_16x16x32_bf16 v[16:19], v[128:131], v[218:221], v[16:19]
	v_mfma_f32_16x16x32_bf16 v[4:7], v[112:115], v[226:229], v[4:7]
	v_mfma_f32_16x16x32_bf16 v[0:3], v[128:131], v[226:229], v[0:3]
	v_mfma_f32_16x16x32_bf16 v[52:55], v[116:119], v[188:191], v[52:55]
	v_mfma_f32_16x16x32_bf16 v[48:51], v[140:143], v[188:191], v[48:51]
	v_mfma_f32_16x16x32_bf16 v[36:39], v[116:119], v[202:205], v[36:39]
	v_mfma_f32_16x16x32_bf16 v[32:35], v[140:143], v[202:205], v[32:35]
	v_mfma_f32_16x16x32_bf16 v[20:23], v[116:119], v[222:225], v[20:23]
	v_mfma_f32_16x16x32_bf16 v[16:19], v[140:143], v[222:225], v[16:19]
	v_mfma_f32_16x16x32_bf16 v[4:7], v[116:119], v[230:233], v[4:7]
	v_mfma_f32_16x16x32_bf16 v[0:3], v[140:143], v[230:233], v[0:3]
	s_setprio 0
	s_barrier
	s_add_i32 s17, 0, 0x18000
	s_add_i32 s24, 0, 0x1c000
	v_add_u32_e32 v100, s17, v197
	v_add_u32_e32 v140, s24, v197
	ds_read_b128 v[72:75], v100
	ds_read_b128 v[84:87], v100 offset:1024
	ds_read_b128 v[96:99], v100 offset:2048
	ds_read_b128 v[100:103], v100 offset:3072
	ds_read_b128 v[112:115], v140
	ds_read_b128 v[116:119], v140 offset:1024
	ds_read_b128 v[128:131], v140 offset:2048
	ds_read_b128 v[140:143], v140 offset:3072
	s_add_u32 s14, s40, 0x40000
	s_addc_u32 s15, s41, 0
	s_mov_b32 m0, s74
	v_lshl_add_u64 v[240:241], s[14:15], 0, v[160:161]
	ds_read_b128 v[184:187], v200 offset:32768
	ds_read_b128 v[188:191], v200 offset:33792
	ds_read_b128 v[192:195], v200 offset:34816
	ds_read_b128 v[202:205], v200 offset:35840
	ds_read_b128 v[218:221], v200 offset:36864
	ds_read_b128 v[222:225], v200 offset:37888
	ds_read_b128 v[226:229], v200 offset:38912
	ds_read_b128 v[230:233], v200 offset:39936
	global_load_lds_dwordx4 v[240:241], off
	v_lshl_add_u64 v[240:241], s[14:15], 0, v[164:165]
	s_mov_b32 m0, s75
	s_nop 0
	global_load_lds_dwordx4 v[240:241], off
	s_waitcnt vmcnt(8)
	s_waitcnt lgkmcnt(0)
	s_barrier
	s_setprio 1
	s_waitcnt lgkmcnt(0)
	v_mfma_f32_16x16x32_bf16 v[156:159], v[72:75], v[184:187], v[156:159]
	v_mfma_f32_16x16x32_bf16 v[152:155], v[96:99], v[184:187], v[152:155]
	v_mfma_f32_16x16x32_bf16 v[136:139], v[72:75], v[192:195], v[136:139]
	v_mfma_f32_16x16x32_bf16 v[132:135], v[96:99], v[192:195], v[132:135]
	v_mfma_f32_16x16x32_bf16 v[108:111], v[72:75], v[218:221], v[108:111]
	v_mfma_f32_16x16x32_bf16 v[104:107], v[96:99], v[218:221], v[104:107]
	v_mfma_f32_16x16x32_bf16 v[80:83], v[72:75], v[226:229], v[80:83]
	v_mfma_f32_16x16x32_bf16 v[76:79], v[96:99], v[226:229], v[76:79]
	v_mfma_f32_16x16x32_bf16 v[156:159], v[84:87], v[188:191], v[156:159]
	v_mfma_f32_16x16x32_bf16 v[152:155], v[100:103], v[188:191], v[152:155]
	v_mfma_f32_16x16x32_bf16 v[136:139], v[84:87], v[202:205], v[136:139]
	v_mfma_f32_16x16x32_bf16 v[132:135], v[100:103], v[202:205], v[132:135]
	v_mfma_f32_16x16x32_bf16 v[108:111], v[84:87], v[222:225], v[108:111]
	v_mfma_f32_16x16x32_bf16 v[104:107], v[100:103], v[222:225], v[104:107]
	v_mfma_f32_16x16x32_bf16 v[80:83], v[84:87], v[230:233], v[80:83]
	v_mfma_f32_16x16x32_bf16 v[76:79], v[100:103], v[230:233], v[76:79]
	s_setprio 0
	s_setprio 1
	v_mfma_f32_16x16x32_bf16 v[148:151], v[112:115], v[184:187], v[148:151]
	v_mfma_f32_16x16x32_bf16 v[144:147], v[128:131], v[184:187], v[144:147]
	v_mfma_f32_16x16x32_bf16 v[124:127], v[112:115], v[192:195], v[124:127]
	v_mfma_f32_16x16x32_bf16 v[120:123], v[128:131], v[192:195], v[120:123]
	v_mfma_f32_16x16x32_bf16 v[92:95], v[112:115], v[218:221], v[92:95]
	v_mfma_f32_16x16x32_bf16 v[88:91], v[128:131], v[218:221], v[88:91]
	v_mfma_f32_16x16x32_bf16 v[68:71], v[112:115], v[226:229], v[68:71]
	v_mfma_f32_16x16x32_bf16 v[64:67], v[128:131], v[226:229], v[64:67]
	v_mfma_f32_16x16x32_bf16 v[148:151], v[116:119], v[188:191], v[148:151]
	v_mfma_f32_16x16x32_bf16 v[144:147], v[140:143], v[188:191], v[144:147]
	v_mfma_f32_16x16x32_bf16 v[124:127], v[116:119], v[202:205], v[124:127]
	v_mfma_f32_16x16x32_bf16 v[120:123], v[140:143], v[202:205], v[120:123]
	v_mfma_f32_16x16x32_bf16 v[92:95], v[116:119], v[222:225], v[92:95]
	v_mfma_f32_16x16x32_bf16 v[88:91], v[140:143], v[222:225], v[88:91]
	v_mfma_f32_16x16x32_bf16 v[68:71], v[116:119], v[230:233], v[68:71]
	v_mfma_f32_16x16x32_bf16 v[64:67], v[140:143], v[230:233], v[64:67]
	s_setprio 0
	s_barrier
; #define PG8_STAGE(bufoff, gbase, voff) do { _Pragma("unroll") for (int _i = 0; _i < 2; ++_i) \
;         __builtin_amdgcn_global_load_lds((const unsigned*)((const char*)(gbase) + (voff)[_i]), (PG8_LAS unsigned*)(lds + (bufoff) + ldsw + _i * 8192), 16, 0, 0); } while (0)
; #define PG8_LDA(dst, b, h) do { _Pragma("unroll") for (int m = 0; m < 4; ++m) _Pragma("unroll") for (int k = 0; k < 2; ++k) dst[m][k] = *(const PG8_LAS bf16x8*)(lds + PG8_SA(b, h) + aoff + m * 2048 + k * 1024); } while (0)
; #define PG8_MMA(ai, bj, At, Bt) do { __builtin_amdgcn_s_setprio(1); _Pragma("unroll") for (int m = 0; m < 4; ++m) _Pragma("unroll") for (int n = 0; n < 2; ++n) _Pragma("unroll") for (int k = 0; k < 2; ++k) \
;         acc[ai][bj][m][n] = __builtin_amdgcn_mfma_f32_16x16x32_bf16(Bt[n][k], At[m][k], acc[ai][bj][m][n], 0, 0, 0); __builtin_amdgcn_s_setprio(0); } while (0)
; #define PG8_WAIT_V(n) asm volatile("s_waitcnt vmcnt(" #n ")" ::: "memory")
; #define PG8_WAIT_L(n) asm volatile("s_waitcnt lgkmcnt(" #n ")" ::: "memory")
; #define PG8_BAR __builtin_amdgcn_s_barrier()
; #define PG8_SCHED __builtin_amdgcn_sched_barrier(0)
; template <class Epi, class Sched, bool ALIGN_EPI = false, bool SP2 = false>
; __device__ __forceinline__ void gemm_phase(PG8_LAS unsigned char* lds, const Gemm g, const Sched& S, const Epi& E) {
;     ...
;         for (int t = 0; t < nt; t += 2) {
;             const bool last = (t == nt - 2);
;     ...
;             PG8_LDA(At, 1, 1); PG8_STAGE(PG8_SB(1, 0), b3, voffB); PG8_STAGE(PG8_SB(1, 1), b3 + hstep, voffB); PG8_STAGE(PG8_SA(1, 0), a3, voffA);
;             PG8_WAIT_V(8); PG8_WAIT_L(0); PG8_BAR; PG8_MMA(1, 0, At, B0); PG8_MMA(1, 1, At, B1); PG8_BAR; PG8_SCHED;
	s_add_i32 s14, s17, s51
	v_lshl_add_u64 v[206:207], v[206:207], 0, s[46:47]
	s_mov_b32 m0, s14
	ds_read_b128 v[184:187], v200 offset:49152
	ds_read_b128 v[188:191], v200 offset:50176
	ds_read_b128 v[192:195], v200 offset:51200
	ds_read_b128 v[202:205], v200 offset:52224
	ds_read_b128 v[218:221], v200 offset:53248
	ds_read_b128 v[222:225], v200 offset:54272
	ds_read_b128 v[226:229], v200 offset:55296
	ds_read_b128 v[230:233], v200 offset:56320
	global_load_lds_dwordx4 v[206:207], off
	s_add_i32 m0, s14, 0x2000
	s_add_u32 s14, s18, 0x40080
	v_lshl_add_u64 v[206:207], v[234:235], 0, s[46:47]
	s_addc_u32 s15, s19, 0
	s_add_i32 s17, s24, s51
	global_load_lds_dwordx4 v[206:207], off
	v_lshl_add_u64 v[206:207], s[14:15], 0, v[162:163]
	s_mov_b32 m0, s17
	s_nop 0
	global_load_lds_dwordx4 v[206:207], off
	v_lshl_add_u64 v[206:207], s[14:15], 0, v[166:167]
	s_add_i32 m0, s17, 0x2000
	s_nop 0
	global_load_lds_dwordx4 v[206:207], off
	v_lshl_add_u64 v[206:207], v[236:237], 0, s[46:47]
	s_mov_b32 m0, s78
	s_nop 0
	global_load_lds_dwordx4 v[206:207], off
	v_lshl_add_u64 v[206:207], v[238:239], 0, s[46:47]
	s_mov_b32 m0, s79
	s_nop 0
	global_load_lds_dwordx4 v[206:207], off
	s_waitcnt vmcnt(8)
	s_waitcnt lgkmcnt(0)
	s_barrier
	s_setprio 1
	s_waitcnt lgkmcnt(0)
	v_mfma_f32_16x16x32_bf16 v[60:63], v[72:75], v[184:187], v[60:63]
	v_mfma_f32_16x16x32_bf16 v[56:59], v[96:99], v[184:187], v[56:59]
	v_mfma_f32_16x16x32_bf16 v[44:47], v[72:75], v[192:195], v[44:47]
	v_mfma_f32_16x16x32_bf16 v[40:43], v[96:99], v[192:195], v[40:43]
	v_mfma_f32_16x16x32_bf16 v[28:31], v[72:75], v[218:221], v[28:31]
	v_mfma_f32_16x16x32_bf16 v[24:27], v[96:99], v[218:221], v[24:27]
	v_mfma_f32_16x16x32_bf16 v[12:15], v[72:75], v[226:229], v[12:15]
	v_mfma_f32_16x16x32_bf16 v[8:11], v[96:99], v[226:229], v[8:11]
	v_mfma_f32_16x16x32_bf16 v[60:63], v[84:87], v[188:191], v[60:63]
	v_mfma_f32_16x16x32_bf16 v[56:59], v[100:103], v[188:191], v[56:59]
	v_mfma_f32_16x16x32_bf16 v[44:47], v[84:87], v[202:205], v[44:47]
	v_mfma_f32_16x16x32_bf16 v[40:43], v[100:103], v[202:205], v[40:43]
	v_mfma_f32_16x16x32_bf16 v[28:31], v[84:87], v[222:225], v[28:31]
	v_mfma_f32_16x16x32_bf16 v[24:27], v[100:103], v[222:225], v[24:27]
	v_mfma_f32_16x16x32_bf16 v[12:15], v[84:87], v[230:233], v[12:15]
	v_mfma_f32_16x16x32_bf16 v[8:11], v[100:103], v[230:233], v[8:11]
	s_setprio 0
	s_setprio 1
	v_mfma_f32_16x16x32_bf16 v[52:55], v[112:115], v[184:187], v[52:55]
	v_mfma_f32_16x16x32_bf16 v[48:51], v[128:131], v[184:187], v[48:51]
	v_mfma_f32_16x16x32_bf16 v[36:39], v[112:115], v[192:195], v[36:39]
	v_mfma_f32_16x16x32_bf16 v[32:35], v[128:131], v[192:195], v[32:35]
	v_mfma_f32_16x16x32_bf16 v[20:23], v[112:115], v[218:221], v[20:23]
	v_mfma_f32_16x16x32_bf16 v[16:19], v[128:131], v[218:221], v[16:19]
	v_mfma_f32_16x16x32_bf16 v[4:7], v[112:115], v[226:229], v[4:7]
	v_mfma_f32_16x16x32_bf16 v[0:3], v[128:131], v[226:229], v[0:3]
	v_mfma_f32_16x16x32_bf16 v[52:55], v[116:119], v[188:191], v[52:55]
	v_mfma_f32_16x16x32_bf16 v[48:51], v[140:143], v[188:191], v[48:51]
	v_mfma_f32_16x16x32_bf16 v[36:39], v[116:119], v[202:205], v[36:39]
	v_mfma_f32_16x16x32_bf16 v[32:35], v[140:143], v[202:205], v[32:35]
	v_mfma_f32_16x16x32_bf16 v[20:23], v[116:119], v[222:225], v[20:23]
	v_mfma_f32_16x16x32_bf16 v[16:19], v[140:143], v[222:225], v[16:19]
	v_mfma_f32_16x16x32_bf16 v[4:7], v[116:119], v[230:233], v[4:7]
	v_mfma_f32_16x16x32_bf16 v[0:3], v[140:143], v[230:233], v[0:3]
	s_setprio 0
	s_barrier
	s_add_i32 s16, s16, 2
	s_add_u32 s38, s38, 0x100
	s_addc_u32 s39, s39, 0
	s_add_u32 s72, s72, 0x100
	s_addc_u32 s33, s33, 0
	s_cmp_gt_u32 s16, 13
	s_cbranch_scc0 .LBB0_637
	s_and_b64 vcc, exec, s[48:49]
	s_cbranch_vccz .LBB0_640
	s_barrier

; __device__ __forceinline__ unsigned cvt_pk_bf16(float lo, float hi) { unsigned r; asm volatile("v_cvt_pk_bf16_f32 %0, %1, %2" : "=v"(r) : "v"(lo), "v"(hi)); return r; }
; __device__ __forceinline__ void st16_wt(void* p, u32x4 v) { asm volatile("global_store_dwordx4 %0, %1, off sc1\n\ts_nop 1" :: "v"(p), "v"(v) : "memory"); }
;     __device__ __forceinline__ void operator()(const f32x4 (&acc)[2][2][4][2], const Unit& u, int wr, int wc, int fr, int fq) const {
;     ...
;                     bf16_t* rowp = base + (size_t)row * 1024;
; #pragma unroll
;                     for (int bj = 0; bj < 2; ++bj) { const f32x4 v0 = v[bj][0] * rs * gg[bj][0], v1 = v[bj][1] * rs * gg[bj][1];
;                         u32x4 w; w.x = cvt_pk_bf16(v0[0], v0[1]); w.y = cvt_pk_bf16(v0[2], v0[3]); w.z = cvt_pk_bf16(v1[0], v1[1]); w.w = cvt_pk_bf16(v1[2], v1[3]);
;                         st16_wt(rowp + 32 * bj, w); } }
.LBB0_680:
	s_nop 0
	v_pk_mul_f32 v[14:15], v[14:15], v[18:19] op_sel_hi:[1,0]
	v_pk_mul_f32 v[12:13], v[12:13], v[18:19] op_sel_hi:[1,0]
	v_pk_mul_f32 v[10:11], v[10:11], v[18:19] op_sel_hi:[1,0]
	v_pk_mul_f32 v[8:9], v[8:9], v[18:19] op_sel_hi:[1,0]
	s_mov_b64 s[14:15], 0x58000
	v_pk_mul_f32 v[14:15], v[74:75], v[14:15]
	v_pk_mul_f32 v[12:13], v[72:73], v[12:13]
	v_pk_mul_f32 v[22:23], v[86:87], v[10:11]
	v_pk_mul_f32 v[10:11], v[84:85], v[8:9]
	v_cvt_pk_bf16_f32 v8, v12, v13
	v_cvt_pk_bf16_f32 v9, v14, v15
	v_pk_mul_f32 v[4:5], v[4:5], v[18:19] op_sel_hi:[1,0]
	v_pk_mul_f32 v[2:3], v[2:3], v[18:19] op_sel_hi:[1,0]
	v_pk_mul_f32 v[0:1], v[0:1], v[18:19] op_sel_hi:[1,0]
	v_lshl_add_u64 v[20:21], v[16:17], 0, s[14:15]
	v_cvt_pk_bf16_f32 v10, v10, v11
	v_cvt_pk_bf16_f32 v11, v22, v23
	v_pk_mul_f32 v[6:7], v[6:7], v[18:19] op_sel_hi:[1,0]
	global_store_dwordx4 v[20:21], v[8:11], off sc1
	s_nop 1
	v_pk_mul_f32 v[4:5], v[96:97], v[4:5]
	v_pk_mul_f32 v[8:9], v[114:115], v[2:3]
	v_pk_mul_f32 v[2:3], v[112:113], v[0:1]
	s_mov_b64 s[14:15], 0x58040
	v_pk_mul_f32 v[6:7], v[98:99], v[6:7]
	v_cvt_pk_bf16_f32 v0, v4, v5
	v_lshl_add_u64 v[4:5], v[16:17], 0, s[14:15]
	v_cvt_pk_bf16_f32 v1, v6, v7
	v_cvt_pk_bf16_f32 v2, v2, v3
	v_cvt_pk_bf16_f32 v3, v8, v9
	s_andn2_b64 vcc, exec, s[36:37]
	global_store_dwordx4 v[4:5], v[0:3], off sc1
	s_mov_b32 s100, 1
	s_nop 1
	s_mov_b64 s[18:19], -1
	s_cbranch_vccnz .LBB0_629
	s_andn2_b64 vcc, exec, s[4:5]
	s_cbranch_vccnz .LBB0_628
	s_barrier
	s_branch .LBB0_628
